# sample attention: all 8 K fragment loads of a tile issued up front (prologue de-serialisation), on top of prompt tile-step rewrite
# speedup vs baseline: 1.0035x; 1.0035x over previous
.LBB0_66:
	v_ashrrev_i32_e32 v163, 31, v162
	v_lshlrev_b64 v[2:3], 12, v[162:163]
	v_lshl_add_u64 v[14:15], v[160:161], 0, v[2:3]
	global_load_dwordx4 v[2:5], v[14:15], off
	global_load_dwordx4 v[6:9], v[14:15], off offset:32
	global_load_dwordx4 v[10:13], v[14:15], off offset:64
	global_load_dwordx4 v[128:131], v[14:15], off offset:96
	global_load_dwordx4 v[236:239], v[14:15], off offset:128
	global_load_dwordx4 v[240:243], v[14:15], off offset:160
	global_load_dwordx4 v[132:135], v[14:15], off offset:192
	global_load_dwordx4 v[214:217], v[14:15], off offset:224
	s_mov_b32 s0, 0x8000
	s_waitcnt vmcnt(7)
	v_mfma_f32_32x32x16_bf16 v[80:95], v[2:5], v[96:99], 0
	s_waitcnt vmcnt(6)
	v_mfma_f32_32x32x16_bf16 v[80:95], v[6:9], v[100:103], v[80:95]
	s_waitcnt vmcnt(5)
	v_mfma_f32_32x32x16_bf16 v[80:95], v[10:13], v[104:107], v[80:95]
	global_load_dwordx2 v[140:141], v[164:165], off
	global_load_dwordx2 v[142:143], v[164:165], off offset:16
	global_load_dwordx2 v[10:11], v[164:165], off offset:32
	global_load_dwordx2 v[12:13], v[164:165], off offset:48
	s_waitcnt vmcnt(8)
	v_mfma_f32_32x32x16_bf16 v[80:95], v[128:131], v[108:111], v[80:95]
	v_add_co_u32_e32 v130, vcc, s0, v164
	s_mov_b32 s0, 0x11000
	s_nop 0
	v_addc_co_u32_e32 v131, vcc, 0, v165, vcc
	v_add_co_u32_e32 v218, vcc, s0, v164
	s_mov_b32 s0, 0x19000
	s_nop 0
	v_addc_co_u32_e32 v219, vcc, 0, v165, vcc
	s_waitcnt vmcnt(7)
	v_mfma_f32_32x32x16_bf16 v[80:95], v[236:239], v[112:115], v[80:95]
	v_add_co_u32_e32 v4, vcc, s0, v164
	v_cmp_lt_i32_e64 s[0:1], s64, v212
	s_nop 0
	v_addc_co_u32_e32 v5, vcc, 0, v165, vcc
	v_cmp_gt_i32_e32 vcc, s61, v212
	s_waitcnt vmcnt(6)
	v_mfma_f32_32x32x16_bf16 v[80:95], v[240:243], v[116:119], v[80:95]
	global_load_dwordx2 v[144:145], v[130:131], off offset:2048
	global_load_dwordx2 v[146:147], v[130:131], off offset:2064
	global_load_dwordx2 v[128:129], v[130:131], off offset:2080
	s_nop 0
	global_load_dwordx2 v[130:131], v[130:131], off offset:2096
	s_nop 0
	global_load_dwordx2 v[136:137], v[218:219], off
	global_load_dwordx2 v[138:139], v[218:219], off offset:16
	global_load_dwordx2 v[6:7], v[218:219], off offset:32
	global_load_dwordx2 v[8:9], v[218:219], off offset:48
	s_waitcnt vmcnt(13)
	v_mfma_f32_32x32x16_bf16 v[80:95], v[132:135], v[120:123], v[80:95]
	global_load_dwordx2 v[132:133], v[4:5], off offset:2048
	global_load_dwordx2 v[134:135], v[4:5], off offset:2064
	global_load_dwordx2 v[2:3], v[4:5], off offset:2080
	s_nop 0
	global_load_dwordx2 v[4:5], v[4:5], off offset:2096
	s_waitcnt vmcnt(12)
	v_mfma_f32_32x32x16_bf16 v[80:95], v[214:217], v[124:127], v[80:95]
	s_and_saveexec_b64 s[12:13], s[0:1]
	s_cbranch_execz .LBB0_68
	v_add_u32_e32 v0, v148, v212
	v_med3_i32 v14, v0, s39, 63
	s_movk_i32 s0, 0xff7f
	v_lshl_add_u32 v163, v14, 2, s66
	v_med3_i32 v14, v0, s0, 62
	s_movk_i32 s0, 0xff7e
	v_lshl_add_u32 v213, v14, 2, s66
	v_med3_i32 v14, v0, s0, 61
	s_movk_i32 s0, 0xff7d
	v_lshl_add_u32 v223, v14, 2, s66
	v_med3_i32 v14, v0, s0, 60
	s_movk_i32 s0, 0xff78
	v_lshl_add_u32 v227, v14, 2, s66
	v_med3_i32 v14, v0, s0, 55
	s_movk_i32 s0, 0xff77
	v_lshl_add_u32 v232, v14, 2, s66
	v_med3_i32 v14, v0, s0, 54
	s_movk_i32 s0, 0xff76
	v_lshl_add_u32 v233, v14, 2, s66
	v_med3_i32 v14, v0, s0, 53
	s_movk_i32 s0, 0xff75
	v_lshl_add_u32 v234, v14, 2, s66
	v_med3_i32 v14, v0, s0, 52
	s_movk_i32 s0, 0xff70
	v_lshl_add_u32 v235, v14, 2, s66
	v_med3_i32 v14, v0, s0, 47
	s_movk_i32 s0, 0xff6f
	v_med3_i32 v15, v0, s0, 46
	s_movk_i32 s0, 0xff6e
	v_med3_i32 v214, v0, s0, 45
	s_movk_i32 s0, 0xff6d
	v_med3_i32 v215, v0, s0, 44
	s_movk_i32 s0, 0xff68
	v_med3_i32 v216, v0, s0, 39
	s_movk_i32 s0, 0xff67
	v_med3_i32 v217, v0, s0, 38
	s_movk_i32 s0, 0xff66
	v_med3_i32 v218, v0, s0, 37
	s_movk_i32 s0, 0xff65
	v_lshl_add_u32 v14, v14, 2, s66
	v_lshl_add_u32 v15, v15, 2, s66
	v_lshl_add_u32 v214, v214, 2, s66
	v_lshl_add_u32 v215, v215, 2, s66
	v_lshl_add_u32 v216, v216, 2, s66
	v_lshl_add_u32 v217, v217, 2, s66
	v_lshl_add_u32 v218, v218, 2, s66
	v_med3_i32 v0, v0, s0, 36
	v_lshl_add_u32 v0, v0, 2, s66
	ds_read_b32 v14, v14 offset:576
	ds_read_b32 v15, v15 offset:580
	ds_read_b32 v214, v214 offset:584
	ds_read_b32 v215, v215 offset:588
	ds_read_b32 v216, v216 offset:608
	ds_read_b32 v217, v217 offset:612
	ds_read_b32 v218, v218 offset:616
	ds_read_b32 v219, v0 offset:620
	ds_read_b32 v224, v163 offset:512
	ds_read_b32 v225, v213 offset:516
	ds_read_b32 v226, v223 offset:520
	ds_read_b32 v227, v227 offset:524
	ds_read_b32 v232, v232 offset:544
	ds_read_b32 v233, v233 offset:548
	ds_read_b32 v234, v234 offset:552
	ds_read_b32 v235, v235 offset:556
	s_waitcnt lgkmcnt(8)
	v_pk_add_f32 v[94:95], v[94:95], v[218:219]
	v_pk_add_f32 v[92:93], v[92:93], v[216:217]
	v_pk_add_f32 v[90:91], v[90:91], v[214:215]
	v_pk_add_f32 v[88:89], v[88:89], v[14:15]
	s_waitcnt lgkmcnt(0)
	v_pk_add_f32 v[86:87], v[86:87], v[234:235]
	v_pk_add_f32 v[84:85], v[84:85], v[232:233]
	v_pk_add_f32 v[82:83], v[82:83], v[226:227]
	v_pk_add_f32 v[80:81], v[80:81], v[224:225]
